# P3 hook: waves 4-7 run the rescale hook before the previous iteration's last barrier so both halves' hooks overlap
# speedup vs baseline: 1.0214x; 1.0021x over previous
.LBB0_597:
	s_and_b32 s2, s64, 0x7ffffff6
	s_cmp_lg_u32 s2, 16
	s_cselect_b64 s[66:67], -1, 0
	s_or_b64 s[66:67], s[62:63], s[66:67]
	s_and_b64 vcc, exec, s[66:67]
	s_cbranch_vccnz .LBB0_599
	s_and_b64 vcc, exec, s[18:19]
	s_cbranch_vccz .LBB0_599
	s_cmp_eq_u32 s64, 16
	s_cselect_b32 s99, 0, 1
	s_add_i32 s99, s98, s99
	s_lshl_b32 s99, s99, 17
	s_add_u32 s100, s38, 0xba00000
	s_addc_u32 s101, s39, 0
	s_add_u32 s100, s100, s99
	s_addc_u32 s101, s101, 0
	v_lshrrev_b32_e32 v2, 6, v175
	v_mul_u32_u24_e32 v2, 0x3c00, v2
	v_lshl_add_u32 v2, v175, 4, v2
	v_mov_b32_e32 v3, 0
	v_lshl_add_u64 v[2:3], s[100:101], 0, v[2:3]
	s_mov_b64 s[100:101], 0x20000
	v_lshl_add_u64 v[254:255], v[2:3], 0, s[100:101]
	global_load_dwordx4 v[132:135], v[2:3], off
	global_load_dwordx4 v[136:139], v[2:3], off offset:1024
	global_load_dwordx4 v[140:143], v[254:255], off
	global_load_dwordx4 v[188:191], v[254:255], off offset:1024
	v_lshl_add_u64 v[2:3], v[2:3], 0, s[20:21]
	v_lshl_add_u64 v[254:255], v[254:255], 0, s[20:21]
	global_load_dwordx4 v[192:195], v[2:3], off
	global_load_dwordx4 v[196:199], v[2:3], off offset:1024
	global_load_dwordx4 v[200:203], v[254:255], off
	global_load_dwordx4 v[204:207], v[254:255], off offset:1024
	v_lshl_add_u64 v[2:3], v[2:3], 0, s[20:21]
	v_lshl_add_u64 v[254:255], v[254:255], 0, s[20:21]
	global_load_dwordx4 v[208:211], v[2:3], off
	global_load_dwordx4 v[212:215], v[2:3], off offset:1024
	global_load_dwordx4 v[216:219], v[254:255], off
	global_load_dwordx4 v[220:223], v[254:255], off offset:1024
	v_lshl_add_u64 v[2:3], v[2:3], 0, s[20:21]
	v_lshl_add_u64 v[254:255], v[254:255], 0, s[20:21]
	global_load_dwordx4 v[224:227], v[2:3], off
	global_load_dwordx4 v[228:231], v[2:3], off offset:1024
	global_load_dwordx4 v[232:235], v[254:255], off
	global_load_dwordx4 v[236:239], v[254:255], off offset:1024
	v_lshl_add_u64 v[2:3], v[2:3], 0, s[20:21]
	v_lshl_add_u64 v[254:255], v[254:255], 0, s[20:21]
	s_waitcnt vmcnt(12)
	v_lshlrev_b32_e32 v178, 16, v140
	v_and_b32_e32 v179, 0xffff0000, v140
	v_lshlrev_b32_e32 v180, 16, v141
	v_and_b32_e32 v181, 0xffff0000, v141
	v_lshlrev_b32_e32 v182, 16, v142
	v_and_b32_e32 v183, 0xffff0000, v142
	v_lshlrev_b32_e32 v184, 16, v143
	v_and_b32_e32 v185, 0xffff0000, v143
	v_rcp_f32_e32 v178, v178
	v_rcp_f32_e32 v179, v179
	v_rcp_f32_e32 v180, v180
	v_rcp_f32_e32 v181, v181
	v_rcp_f32_e32 v182, v182
	v_rcp_f32_e32 v183, v183
	v_rcp_f32_e32 v184, v184
	v_rcp_f32_e32 v185, v185
	v_lshlrev_b32_e32 v140, 16, v132
	v_and_b32_e32 v141, 0xffff0000, v132
	v_lshlrev_b32_e32 v142, 16, v133
	v_and_b32_e32 v143, 0xffff0000, v133
	v_lshlrev_b32_e32 v132, 16, v134
	v_and_b32_e32 v133, 0xffff0000, v134
	v_lshlrev_b32_e32 v134, 16, v135
	v_and_b32_e32 v135, 0xffff0000, v135
	v_pk_mul_f32 v[178:179], v[178:179], v[140:141]
	v_pk_mul_f32 v[180:181], v[180:181], v[142:143]
	v_pk_mul_f32 v[182:183], v[182:183], v[132:133]
	v_pk_mul_f32 v[184:185], v[184:185], v[134:135]
	v_pk_mul_f32 v[128:129], v[128:129], v[178:179]
	v_pk_mul_f32 v[130:131], v[130:131], v[180:181]
	v_pk_mul_f32 v[124:125], v[124:125], v[182:183]
	v_pk_mul_f32 v[126:127], v[126:127], v[184:185]
	v_lshlrev_b32_e32 v246, 16, v188
	v_and_b32_e32 v247, 0xffff0000, v188
	v_lshlrev_b32_e32 v248, 16, v189
	v_and_b32_e32 v249, 0xffff0000, v189
	v_lshlrev_b32_e32 v250, 16, v190
	v_and_b32_e32 v251, 0xffff0000, v190
	v_lshlrev_b32_e32 v252, 16, v191
	v_and_b32_e32 v253, 0xffff0000, v191
	v_rcp_f32_e32 v246, v246
	v_rcp_f32_e32 v247, v247
	v_rcp_f32_e32 v248, v248
	v_rcp_f32_e32 v249, v249
	v_rcp_f32_e32 v250, v250
	v_rcp_f32_e32 v251, v251
	v_rcp_f32_e32 v252, v252
	v_rcp_f32_e32 v253, v253
	v_lshlrev_b32_e32 v188, 16, v136
	v_and_b32_e32 v189, 0xffff0000, v136
	v_lshlrev_b32_e32 v190, 16, v137
	v_and_b32_e32 v191, 0xffff0000, v137
	v_lshlrev_b32_e32 v136, 16, v138
	v_and_b32_e32 v137, 0xffff0000, v138
	v_lshlrev_b32_e32 v138, 16, v139
	v_and_b32_e32 v139, 0xffff0000, v139
	v_pk_mul_f32 v[246:247], v[246:247], v[188:189]
	v_pk_mul_f32 v[248:249], v[248:249], v[190:191]
	v_pk_mul_f32 v[250:251], v[250:251], v[136:137]
	v_pk_mul_f32 v[252:253], v[252:253], v[138:139]
	v_pk_mul_f32 v[120:121], v[120:121], v[246:247]
	v_pk_mul_f32 v[122:123], v[122:123], v[248:249]
	v_pk_mul_f32 v[116:117], v[116:117], v[250:251]
	v_pk_mul_f32 v[118:119], v[118:119], v[252:253]
	global_load_dwordx4 v[132:135], v[2:3], off
	global_load_dwordx4 v[136:139], v[2:3], off offset:1024
	global_load_dwordx4 v[140:143], v[254:255], off
	global_load_dwordx4 v[188:191], v[254:255], off offset:1024
	v_lshl_add_u64 v[2:3], v[2:3], 0, s[20:21]
	v_lshl_add_u64 v[254:255], v[254:255], 0, s[20:21]
	s_waitcnt vmcnt(12)
	v_lshlrev_b32_e32 v178, 16, v200
	v_and_b32_e32 v179, 0xffff0000, v200
	v_lshlrev_b32_e32 v180, 16, v201
	v_and_b32_e32 v181, 0xffff0000, v201
	v_lshlrev_b32_e32 v182, 16, v202
	v_and_b32_e32 v183, 0xffff0000, v202
	v_lshlrev_b32_e32 v184, 16, v203
	v_and_b32_e32 v185, 0xffff0000, v203
	v_rcp_f32_e32 v178, v178
	v_rcp_f32_e32 v179, v179
	v_rcp_f32_e32 v180, v180
	v_rcp_f32_e32 v181, v181
	v_rcp_f32_e32 v182, v182
	v_rcp_f32_e32 v183, v183
	v_rcp_f32_e32 v184, v184
	v_rcp_f32_e32 v185, v185
	v_lshlrev_b32_e32 v200, 16, v192
	v_and_b32_e32 v201, 0xffff0000, v192
	v_lshlrev_b32_e32 v202, 16, v193
	v_and_b32_e32 v203, 0xffff0000, v193
	v_lshlrev_b32_e32 v192, 16, v194
	v_and_b32_e32 v193, 0xffff0000, v194
	v_lshlrev_b32_e32 v194, 16, v195
	v_and_b32_e32 v195, 0xffff0000, v195
	v_pk_mul_f32 v[178:179], v[178:179], v[200:201]
	v_pk_mul_f32 v[180:181], v[180:181], v[202:203]
	v_pk_mul_f32 v[182:183], v[182:183], v[192:193]
	v_pk_mul_f32 v[184:185], v[184:185], v[194:195]
	v_pk_mul_f32 v[112:113], v[112:113], v[178:179]
	v_pk_mul_f32 v[114:115], v[114:115], v[180:181]
	v_pk_mul_f32 v[108:109], v[108:109], v[182:183]
	v_pk_mul_f32 v[110:111], v[110:111], v[184:185]
	v_lshlrev_b32_e32 v246, 16, v204
	v_and_b32_e32 v247, 0xffff0000, v204
	v_lshlrev_b32_e32 v248, 16, v205
	v_and_b32_e32 v249, 0xffff0000, v205
	v_lshlrev_b32_e32 v250, 16, v206
	v_and_b32_e32 v251, 0xffff0000, v206
	v_lshlrev_b32_e32 v252, 16, v207
	v_and_b32_e32 v253, 0xffff0000, v207
	v_rcp_f32_e32 v246, v246
	v_rcp_f32_e32 v247, v247
	v_rcp_f32_e32 v248, v248
	v_rcp_f32_e32 v249, v249
	v_rcp_f32_e32 v250, v250
	v_rcp_f32_e32 v251, v251
	v_rcp_f32_e32 v252, v252
	v_rcp_f32_e32 v253, v253
	v_lshlrev_b32_e32 v204, 16, v196
	v_and_b32_e32 v205, 0xffff0000, v196
	v_lshlrev_b32_e32 v206, 16, v197
	v_and_b32_e32 v207, 0xffff0000, v197
	v_lshlrev_b32_e32 v196, 16, v198
	v_and_b32_e32 v197, 0xffff0000, v198
	v_lshlrev_b32_e32 v198, 16, v199
	v_and_b32_e32 v199, 0xffff0000, v199
	v_pk_mul_f32 v[246:247], v[246:247], v[204:205]
	v_pk_mul_f32 v[248:249], v[248:249], v[206:207]
	v_pk_mul_f32 v[250:251], v[250:251], v[196:197]
	v_pk_mul_f32 v[252:253], v[252:253], v[198:199]
	v_pk_mul_f32 v[104:105], v[104:105], v[246:247]
	v_pk_mul_f32 v[106:107], v[106:107], v[248:249]
	v_pk_mul_f32 v[100:101], v[100:101], v[250:251]
	v_pk_mul_f32 v[102:103], v[102:103], v[252:253]
	global_load_dwordx4 v[192:195], v[2:3], off
	global_load_dwordx4 v[196:199], v[2:3], off offset:1024
	global_load_dwordx4 v[200:203], v[254:255], off
	global_load_dwordx4 v[204:207], v[254:255], off offset:1024
	v_lshl_add_u64 v[2:3], v[2:3], 0, s[20:21]
	v_lshl_add_u64 v[254:255], v[254:255], 0, s[20:21]
	s_waitcnt vmcnt(12)
	v_lshlrev_b32_e32 v178, 16, v216
	v_and_b32_e32 v179, 0xffff0000, v216
	v_lshlrev_b32_e32 v180, 16, v217
	v_and_b32_e32 v181, 0xffff0000, v217
	v_lshlrev_b32_e32 v182, 16, v218
	v_and_b32_e32 v183, 0xffff0000, v218
	v_lshlrev_b32_e32 v184, 16, v219
	v_and_b32_e32 v185, 0xffff0000, v219
	v_rcp_f32_e32 v178, v178
	v_rcp_f32_e32 v179, v179
	v_rcp_f32_e32 v180, v180
	v_rcp_f32_e32 v181, v181
	v_rcp_f32_e32 v182, v182
	v_rcp_f32_e32 v183, v183
	v_rcp_f32_e32 v184, v184
	v_rcp_f32_e32 v185, v185
	v_lshlrev_b32_e32 v216, 16, v208
	v_and_b32_e32 v217, 0xffff0000, v208
	v_lshlrev_b32_e32 v218, 16, v209
	v_and_b32_e32 v219, 0xffff0000, v209
	v_lshlrev_b32_e32 v208, 16, v210
	v_and_b32_e32 v209, 0xffff0000, v210
	v_lshlrev_b32_e32 v210, 16, v211
	v_and_b32_e32 v211, 0xffff0000, v211
	v_pk_mul_f32 v[178:179], v[178:179], v[216:217]
	v_pk_mul_f32 v[180:181], v[180:181], v[218:219]
	v_pk_mul_f32 v[182:183], v[182:183], v[208:209]
	v_pk_mul_f32 v[184:185], v[184:185], v[210:211]
	v_pk_mul_f32 v[96:97], v[96:97], v[178:179]
	v_pk_mul_f32 v[98:99], v[98:99], v[180:181]
	v_pk_mul_f32 v[92:93], v[92:93], v[182:183]
	v_pk_mul_f32 v[94:95], v[94:95], v[184:185]
	v_lshlrev_b32_e32 v246, 16, v220
	v_and_b32_e32 v247, 0xffff0000, v220
	v_lshlrev_b32_e32 v248, 16, v221
	v_and_b32_e32 v249, 0xffff0000, v221
	v_lshlrev_b32_e32 v250, 16, v222
	v_and_b32_e32 v251, 0xffff0000, v222
	v_lshlrev_b32_e32 v252, 16, v223
	v_and_b32_e32 v253, 0xffff0000, v223
	v_rcp_f32_e32 v246, v246
	v_rcp_f32_e32 v247, v247
	v_rcp_f32_e32 v248, v248
	v_rcp_f32_e32 v249, v249
	v_rcp_f32_e32 v250, v250
	v_rcp_f32_e32 v251, v251
	v_rcp_f32_e32 v252, v252
	v_rcp_f32_e32 v253, v253
	v_lshlrev_b32_e32 v220, 16, v212
	v_and_b32_e32 v221, 0xffff0000, v212
	v_lshlrev_b32_e32 v222, 16, v213
	v_and_b32_e32 v223, 0xffff0000, v213
	v_lshlrev_b32_e32 v212, 16, v214
	v_and_b32_e32 v213, 0xffff0000, v214
	v_lshlrev_b32_e32 v214, 16, v215
	v_and_b32_e32 v215, 0xffff0000, v215
	v_pk_mul_f32 v[246:247], v[246:247], v[220:221]
	v_pk_mul_f32 v[248:249], v[248:249], v[222:223]
	v_pk_mul_f32 v[250:251], v[250:251], v[212:213]
	v_pk_mul_f32 v[252:253], v[252:253], v[214:215]
	v_pk_mul_f32 v[88:89], v[88:89], v[246:247]
	v_pk_mul_f32 v[90:91], v[90:91], v[248:249]
	v_pk_mul_f32 v[84:85], v[84:85], v[250:251]
	v_pk_mul_f32 v[86:87], v[86:87], v[252:253]
	global_load_dwordx4 v[208:211], v[2:3], off
	global_load_dwordx4 v[212:215], v[2:3], off offset:1024
	global_load_dwordx4 v[216:219], v[254:255], off
	global_load_dwordx4 v[220:223], v[254:255], off offset:1024
	v_lshl_add_u64 v[2:3], v[2:3], 0, s[20:21]
	v_lshl_add_u64 v[254:255], v[254:255], 0, s[20:21]
	s_waitcnt vmcnt(12)
	v_lshlrev_b32_e32 v178, 16, v232
	v_and_b32_e32 v179, 0xffff0000, v232
	v_lshlrev_b32_e32 v180, 16, v233
	v_and_b32_e32 v181, 0xffff0000, v233
	v_lshlrev_b32_e32 v182, 16, v234
	v_and_b32_e32 v183, 0xffff0000, v234
	v_lshlrev_b32_e32 v184, 16, v235
	v_and_b32_e32 v185, 0xffff0000, v235
	v_rcp_f32_e32 v178, v178
	v_rcp_f32_e32 v179, v179
	v_rcp_f32_e32 v180, v180
	v_rcp_f32_e32 v181, v181
	v_rcp_f32_e32 v182, v182
	v_rcp_f32_e32 v183, v183
	v_rcp_f32_e32 v184, v184
	v_rcp_f32_e32 v185, v185
	v_lshlrev_b32_e32 v232, 16, v224
	v_and_b32_e32 v233, 0xffff0000, v224
	v_lshlrev_b32_e32 v234, 16, v225
	v_and_b32_e32 v235, 0xffff0000, v225
	v_lshlrev_b32_e32 v224, 16, v226
	v_and_b32_e32 v225, 0xffff0000, v226
	v_lshlrev_b32_e32 v226, 16, v227
	v_and_b32_e32 v227, 0xffff0000, v227
	v_pk_mul_f32 v[178:179], v[178:179], v[232:233]
	v_pk_mul_f32 v[180:181], v[180:181], v[234:235]
	v_pk_mul_f32 v[182:183], v[182:183], v[224:225]
	v_pk_mul_f32 v[184:185], v[184:185], v[226:227]
	v_pk_mul_f32 v[80:81], v[80:81], v[178:179]
	v_pk_mul_f32 v[82:83], v[82:83], v[180:181]
	v_pk_mul_f32 v[76:77], v[76:77], v[182:183]
	v_pk_mul_f32 v[78:79], v[78:79], v[184:185]
	v_lshlrev_b32_e32 v246, 16, v236
	v_and_b32_e32 v247, 0xffff0000, v236
	v_lshlrev_b32_e32 v248, 16, v237
	v_and_b32_e32 v249, 0xffff0000, v237
	v_lshlrev_b32_e32 v250, 16, v238
	v_and_b32_e32 v251, 0xffff0000, v238
	v_lshlrev_b32_e32 v252, 16, v239
	v_and_b32_e32 v253, 0xffff0000, v239
	v_rcp_f32_e32 v246, v246
	v_rcp_f32_e32 v247, v247
	v_rcp_f32_e32 v248, v248
	v_rcp_f32_e32 v249, v249
	v_rcp_f32_e32 v250, v250
	v_rcp_f32_e32 v251, v251
	v_rcp_f32_e32 v252, v252
	v_rcp_f32_e32 v253, v253
	v_lshlrev_b32_e32 v236, 16, v228
	v_and_b32_e32 v237, 0xffff0000, v228
	v_lshlrev_b32_e32 v238, 16, v229
	v_and_b32_e32 v239, 0xffff0000, v229
	v_lshlrev_b32_e32 v228, 16, v230
	v_and_b32_e32 v229, 0xffff0000, v230
	v_lshlrev_b32_e32 v230, 16, v231
	v_and_b32_e32 v231, 0xffff0000, v231
	v_pk_mul_f32 v[246:247], v[246:247], v[236:237]
	v_pk_mul_f32 v[248:249], v[248:249], v[238:239]
	v_pk_mul_f32 v[250:251], v[250:251], v[228:229]
	v_pk_mul_f32 v[252:253], v[252:253], v[230:231]
	v_pk_mul_f32 v[72:73], v[72:73], v[246:247]
	v_pk_mul_f32 v[74:75], v[74:75], v[248:249]
	v_pk_mul_f32 v[68:69], v[68:69], v[250:251]
	v_pk_mul_f32 v[70:71], v[70:71], v[252:253]
	global_load_dwordx4 v[224:227], v[2:3], off
	global_load_dwordx4 v[228:231], v[2:3], off offset:1024
	global_load_dwordx4 v[232:235], v[254:255], off
	global_load_dwordx4 v[236:239], v[254:255], off offset:1024
	s_waitcnt vmcnt(12)
	v_lshlrev_b32_e32 v178, 16, v140
	v_and_b32_e32 v179, 0xffff0000, v140
	v_lshlrev_b32_e32 v180, 16, v141
	v_and_b32_e32 v181, 0xffff0000, v141
	v_lshlrev_b32_e32 v182, 16, v142
	v_and_b32_e32 v183, 0xffff0000, v142
	v_lshlrev_b32_e32 v184, 16, v143
	v_and_b32_e32 v185, 0xffff0000, v143
	v_rcp_f32_e32 v178, v178
	v_rcp_f32_e32 v179, v179
	v_rcp_f32_e32 v180, v180
	v_rcp_f32_e32 v181, v181
	v_rcp_f32_e32 v182, v182
	v_rcp_f32_e32 v183, v183
	v_rcp_f32_e32 v184, v184
	v_rcp_f32_e32 v185, v185
	v_lshlrev_b32_e32 v140, 16, v132
	v_and_b32_e32 v141, 0xffff0000, v132
	v_lshlrev_b32_e32 v142, 16, v133
	v_and_b32_e32 v143, 0xffff0000, v133
	v_lshlrev_b32_e32 v132, 16, v134
	v_and_b32_e32 v133, 0xffff0000, v134
	v_lshlrev_b32_e32 v134, 16, v135
	v_and_b32_e32 v135, 0xffff0000, v135
	v_pk_mul_f32 v[178:179], v[178:179], v[140:141]
	v_pk_mul_f32 v[180:181], v[180:181], v[142:143]
	v_pk_mul_f32 v[182:183], v[182:183], v[132:133]
	v_pk_mul_f32 v[184:185], v[184:185], v[134:135]
	v_pk_mul_f32 v[64:65], v[64:65], v[178:179]
	v_pk_mul_f32 v[66:67], v[66:67], v[180:181]
	v_pk_mul_f32 v[60:61], v[60:61], v[182:183]
	v_pk_mul_f32 v[62:63], v[62:63], v[184:185]
	v_lshlrev_b32_e32 v246, 16, v188
	v_and_b32_e32 v247, 0xffff0000, v188
	v_lshlrev_b32_e32 v248, 16, v189
	v_and_b32_e32 v249, 0xffff0000, v189
	v_lshlrev_b32_e32 v250, 16, v190
	v_and_b32_e32 v251, 0xffff0000, v190
	v_lshlrev_b32_e32 v252, 16, v191
	v_and_b32_e32 v253, 0xffff0000, v191
	v_rcp_f32_e32 v246, v246
	v_rcp_f32_e32 v247, v247
	v_rcp_f32_e32 v248, v248
	v_rcp_f32_e32 v249, v249
	v_rcp_f32_e32 v250, v250
	v_rcp_f32_e32 v251, v251
	v_rcp_f32_e32 v252, v252
	v_rcp_f32_e32 v253, v253
	v_lshlrev_b32_e32 v188, 16, v136
	v_and_b32_e32 v189, 0xffff0000, v136
	v_lshlrev_b32_e32 v190, 16, v137
	v_and_b32_e32 v191, 0xffff0000, v137
	v_lshlrev_b32_e32 v136, 16, v138
	v_and_b32_e32 v137, 0xffff0000, v138
	v_lshlrev_b32_e32 v138, 16, v139
	v_and_b32_e32 v139, 0xffff0000, v139
	v_pk_mul_f32 v[246:247], v[246:247], v[188:189]
	v_pk_mul_f32 v[248:249], v[248:249], v[190:191]
	v_pk_mul_f32 v[250:251], v[250:251], v[136:137]
	v_pk_mul_f32 v[252:253], v[252:253], v[138:139]
	v_pk_mul_f32 v[56:57], v[56:57], v[246:247]
	v_pk_mul_f32 v[58:59], v[58:59], v[248:249]
	v_pk_mul_f32 v[52:53], v[52:53], v[250:251]
	v_pk_mul_f32 v[54:55], v[54:55], v[252:253]
	s_waitcnt vmcnt(8)
	v_lshlrev_b32_e32 v178, 16, v200
	v_and_b32_e32 v179, 0xffff0000, v200
	v_lshlrev_b32_e32 v180, 16, v201
	v_and_b32_e32 v181, 0xffff0000, v201
	v_lshlrev_b32_e32 v182, 16, v202
	v_and_b32_e32 v183, 0xffff0000, v202
	v_lshlrev_b32_e32 v184, 16, v203
	v_and_b32_e32 v185, 0xffff0000, v203
	v_rcp_f32_e32 v178, v178
	v_rcp_f32_e32 v179, v179
	v_rcp_f32_e32 v180, v180
	v_rcp_f32_e32 v181, v181
	v_rcp_f32_e32 v182, v182
	v_rcp_f32_e32 v183, v183
	v_rcp_f32_e32 v184, v184
	v_rcp_f32_e32 v185, v185
	v_lshlrev_b32_e32 v200, 16, v192
	v_and_b32_e32 v201, 0xffff0000, v192
	v_lshlrev_b32_e32 v202, 16, v193
	v_and_b32_e32 v203, 0xffff0000, v193
	v_lshlrev_b32_e32 v192, 16, v194
	v_and_b32_e32 v193, 0xffff0000, v194
	v_lshlrev_b32_e32 v194, 16, v195
	v_and_b32_e32 v195, 0xffff0000, v195
	v_pk_mul_f32 v[178:179], v[178:179], v[200:201]
	v_pk_mul_f32 v[180:181], v[180:181], v[202:203]
	v_pk_mul_f32 v[182:183], v[182:183], v[192:193]
	v_pk_mul_f32 v[184:185], v[184:185], v[194:195]
	v_pk_mul_f32 v[48:49], v[48:49], v[178:179]
	v_pk_mul_f32 v[50:51], v[50:51], v[180:181]
	v_pk_mul_f32 v[44:45], v[44:45], v[182:183]
	v_pk_mul_f32 v[46:47], v[46:47], v[184:185]
	v_lshlrev_b32_e32 v246, 16, v204
	v_and_b32_e32 v247, 0xffff0000, v204
	v_lshlrev_b32_e32 v248, 16, v205
	v_and_b32_e32 v249, 0xffff0000, v205
	v_lshlrev_b32_e32 v250, 16, v206
	v_and_b32_e32 v251, 0xffff0000, v206
	v_lshlrev_b32_e32 v252, 16, v207
	v_and_b32_e32 v253, 0xffff0000, v207
	v_rcp_f32_e32 v246, v246
	v_rcp_f32_e32 v247, v247
	v_rcp_f32_e32 v248, v248
	v_rcp_f32_e32 v249, v249
	v_rcp_f32_e32 v250, v250
	v_rcp_f32_e32 v251, v251
	v_rcp_f32_e32 v252, v252
	v_rcp_f32_e32 v253, v253
	v_lshlrev_b32_e32 v204, 16, v196
	v_and_b32_e32 v205, 0xffff0000, v196
	v_lshlrev_b32_e32 v206, 16, v197
	v_and_b32_e32 v207, 0xffff0000, v197
	v_lshlrev_b32_e32 v196, 16, v198
	v_and_b32_e32 v197, 0xffff0000, v198
	v_lshlrev_b32_e32 v198, 16, v199
	v_and_b32_e32 v199, 0xffff0000, v199
	v_pk_mul_f32 v[246:247], v[246:247], v[204:205]
	v_pk_mul_f32 v[248:249], v[248:249], v[206:207]
	v_pk_mul_f32 v[250:251], v[250:251], v[196:197]
	v_pk_mul_f32 v[252:253], v[252:253], v[198:199]
	v_pk_mul_f32 v[40:41], v[40:41], v[246:247]
	v_pk_mul_f32 v[42:43], v[42:43], v[248:249]
	v_pk_mul_f32 v[36:37], v[36:37], v[250:251]
	v_pk_mul_f32 v[38:39], v[38:39], v[252:253]
	s_waitcnt vmcnt(4)
	v_lshlrev_b32_e32 v178, 16, v216
	v_and_b32_e32 v179, 0xffff0000, v216
	v_lshlrev_b32_e32 v180, 16, v217
	v_and_b32_e32 v181, 0xffff0000, v217
	v_lshlrev_b32_e32 v182, 16, v218
	v_and_b32_e32 v183, 0xffff0000, v218
	v_lshlrev_b32_e32 v184, 16, v219
	v_and_b32_e32 v185, 0xffff0000, v219
	v_rcp_f32_e32 v178, v178
	v_rcp_f32_e32 v179, v179
	v_rcp_f32_e32 v180, v180
	v_rcp_f32_e32 v181, v181
	v_rcp_f32_e32 v182, v182
	v_rcp_f32_e32 v183, v183
	v_rcp_f32_e32 v184, v184
	v_rcp_f32_e32 v185, v185
	v_lshlrev_b32_e32 v216, 16, v208
	v_and_b32_e32 v217, 0xffff0000, v208
	v_lshlrev_b32_e32 v218, 16, v209
	v_and_b32_e32 v219, 0xffff0000, v209
	v_lshlrev_b32_e32 v208, 16, v210
	v_and_b32_e32 v209, 0xffff0000, v210
	v_lshlrev_b32_e32 v210, 16, v211
	v_and_b32_e32 v211, 0xffff0000, v211
	v_pk_mul_f32 v[178:179], v[178:179], v[216:217]
	v_pk_mul_f32 v[180:181], v[180:181], v[218:219]
	v_pk_mul_f32 v[182:183], v[182:183], v[208:209]
	v_pk_mul_f32 v[184:185], v[184:185], v[210:211]
	v_pk_mul_f32 v[32:33], v[32:33], v[178:179]
	v_pk_mul_f32 v[34:35], v[34:35], v[180:181]
	v_pk_mul_f32 v[28:29], v[28:29], v[182:183]
	v_pk_mul_f32 v[30:31], v[30:31], v[184:185]
	v_lshlrev_b32_e32 v246, 16, v220
	v_and_b32_e32 v247, 0xffff0000, v220
	v_lshlrev_b32_e32 v248, 16, v221
	v_and_b32_e32 v249, 0xffff0000, v221
	v_lshlrev_b32_e32 v250, 16, v222
	v_and_b32_e32 v251, 0xffff0000, v222
	v_lshlrev_b32_e32 v252, 16, v223
	v_and_b32_e32 v253, 0xffff0000, v223
	v_rcp_f32_e32 v246, v246
	v_rcp_f32_e32 v247, v247
	v_rcp_f32_e32 v248, v248
	v_rcp_f32_e32 v249, v249
	v_rcp_f32_e32 v250, v250
	v_rcp_f32_e32 v251, v251
	v_rcp_f32_e32 v252, v252
	v_rcp_f32_e32 v253, v253
	v_lshlrev_b32_e32 v220, 16, v212
	v_and_b32_e32 v221, 0xffff0000, v212
	v_lshlrev_b32_e32 v222, 16, v213
	v_and_b32_e32 v223, 0xffff0000, v213
	v_lshlrev_b32_e32 v212, 16, v214
	v_and_b32_e32 v213, 0xffff0000, v214
	v_lshlrev_b32_e32 v214, 16, v215
	v_and_b32_e32 v215, 0xffff0000, v215
	v_pk_mul_f32 v[246:247], v[246:247], v[220:221]
	v_pk_mul_f32 v[248:249], v[248:249], v[222:223]
	v_pk_mul_f32 v[250:251], v[250:251], v[212:213]
	v_pk_mul_f32 v[252:253], v[252:253], v[214:215]
	v_pk_mul_f32 v[24:25], v[24:25], v[246:247]
	v_pk_mul_f32 v[26:27], v[26:27], v[248:249]
	v_pk_mul_f32 v[20:21], v[20:21], v[250:251]
	v_pk_mul_f32 v[22:23], v[22:23], v[252:253]
	s_waitcnt vmcnt(0)
	v_lshlrev_b32_e32 v178, 16, v232
	v_and_b32_e32 v179, 0xffff0000, v232
	v_lshlrev_b32_e32 v180, 16, v233
	v_and_b32_e32 v181, 0xffff0000, v233
	v_lshlrev_b32_e32 v182, 16, v234
	v_and_b32_e32 v183, 0xffff0000, v234
	v_lshlrev_b32_e32 v184, 16, v235
	v_and_b32_e32 v185, 0xffff0000, v235
	v_rcp_f32_e32 v178, v178
	v_rcp_f32_e32 v179, v179
	v_rcp_f32_e32 v180, v180
	v_rcp_f32_e32 v181, v181
	v_rcp_f32_e32 v182, v182
	v_rcp_f32_e32 v183, v183
	v_rcp_f32_e32 v184, v184
	v_rcp_f32_e32 v185, v185
	v_lshlrev_b32_e32 v232, 16, v224
	v_and_b32_e32 v233, 0xffff0000, v224
	v_lshlrev_b32_e32 v234, 16, v225
	v_and_b32_e32 v235, 0xffff0000, v225
	v_lshlrev_b32_e32 v224, 16, v226
	v_and_b32_e32 v225, 0xffff0000, v226
	v_lshlrev_b32_e32 v226, 16, v227
	v_and_b32_e32 v227, 0xffff0000, v227
	v_pk_mul_f32 v[178:179], v[178:179], v[232:233]
	v_pk_mul_f32 v[180:181], v[180:181], v[234:235]
	v_pk_mul_f32 v[182:183], v[182:183], v[224:225]
	v_pk_mul_f32 v[184:185], v[184:185], v[226:227]
	v_pk_mul_f32 v[16:17], v[16:17], v[178:179]
	v_pk_mul_f32 v[18:19], v[18:19], v[180:181]
	v_pk_mul_f32 v[12:13], v[12:13], v[182:183]
	v_pk_mul_f32 v[14:15], v[14:15], v[184:185]
	v_lshlrev_b32_e32 v246, 16, v236
	v_and_b32_e32 v247, 0xffff0000, v236
	v_lshlrev_b32_e32 v248, 16, v237
	v_and_b32_e32 v249, 0xffff0000, v237
	v_lshlrev_b32_e32 v250, 16, v238
	v_and_b32_e32 v251, 0xffff0000, v238
	v_lshlrev_b32_e32 v252, 16, v239
	v_and_b32_e32 v253, 0xffff0000, v239
	v_rcp_f32_e32 v246, v246
	v_rcp_f32_e32 v247, v247
	v_rcp_f32_e32 v248, v248
	v_rcp_f32_e32 v249, v249
	v_rcp_f32_e32 v250, v250
	v_rcp_f32_e32 v251, v251
	v_rcp_f32_e32 v252, v252
	v_rcp_f32_e32 v253, v253
	v_lshlrev_b32_e32 v236, 16, v228
	v_and_b32_e32 v237, 0xffff0000, v228
	v_lshlrev_b32_e32 v238, 16, v229
	v_and_b32_e32 v239, 0xffff0000, v229
	v_lshlrev_b32_e32 v228, 16, v230
	v_and_b32_e32 v229, 0xffff0000, v230
	v_lshlrev_b32_e32 v230, 16, v231
	v_and_b32_e32 v231, 0xffff0000, v231
	v_pk_mul_f32 v[246:247], v[246:247], v[236:237]
	v_pk_mul_f32 v[248:249], v[248:249], v[238:239]
	v_pk_mul_f32 v[250:251], v[250:251], v[228:229]
	v_pk_mul_f32 v[252:253], v[252:253], v[230:231]
	v_pk_mul_f32 v[8:9], v[8:9], v[246:247]
	v_pk_mul_f32 v[10:11], v[10:11], v[248:249]
	v_pk_mul_f32 v[4:5], v[4:5], v[250:251]
	v_pk_mul_f32 v[6:7], v[6:7], v[252:253]
.LBB0_599:
	v_add_u32_e32 v1, s79, v173
	s_add_i32 s2, s64, 2
	ds_read_b128 v[132:135], v1
	ds_read_b128 v[136:139], v1 offset:1024
	ds_read_b128 v[140:143], v1 offset:2048
	ds_read_b128 v[178:181], v1 offset:3072
	v_add_u32_e32 v1, s80, v173
	s_add_u32 s65, s58, s60
	ds_read_b128 v[182:185], v1
	ds_read_b128 v[188:191], v1 offset:1024
	ds_read_b128 v[192:195], v1 offset:2048
	ds_read_b128 v[196:199], v1 offset:3072
	s_addc_u32 s66, s59, s61
	s_add_u32 s65, s65, 0x100
	s_addc_u32 s66, s66, 0
	s_add_u32 s75, s89, s60
	s_addc_u32 s91, s90, s61
	s_cmp_eq_u32 s7, s64
	s_cselect_b32 s67, s51, s66
	s_cselect_b32 s66, s50, s65
	s_cselect_b32 s65, s53, s91
	s_cselect_b32 s64, s52, s75
	v_lshl_add_u64 v[2:3], v[168:169], 0, s[60:61]
	s_add_i32 m0, s69, 0xc000
	ds_read_b128 v[200:203], v174
	ds_read_b128 v[204:207], v174 offset:1024
	ds_read_b128 v[208:211], v174 offset:2048
	ds_read_b128 v[212:215], v174 offset:3072
	ds_read_b128 v[216:219], v174 offset:4096
	ds_read_b128 v[220:223], v174 offset:5120
	ds_read_b128 v[224:227], v174 offset:6144
	ds_read_b128 v[228:231], v174 offset:7168
	global_load_lds_dwordx4 v[2:3], off
	v_lshl_add_u64 v[2:3], v[170:171], 0, s[60:61]
	s_add_i32 m0, s69, 0xe000
	s_nop 0
	global_load_lds_dwordx4 v[2:3], off
	s_waitcnt vmcnt(8)
	s_waitcnt lgkmcnt(0)
	s_barrier
	s_setprio 1
	s_waitcnt lgkmcnt(0)
	v_mfma_f32_16x16x32_bf16 v[128:131], v[132:135], v[200:203], v[128:131]
	v_mfma_f32_16x16x32_bf16 v[124:127], v[140:143], v[200:203], v[124:127]
	v_mfma_f32_16x16x32_bf16 v[112:115], v[132:135], v[208:211], v[112:115]
	v_mfma_f32_16x16x32_bf16 v[108:111], v[140:143], v[208:211], v[108:111]
	v_mfma_f32_16x16x32_bf16 v[96:99], v[132:135], v[216:219], v[96:99]
	v_mfma_f32_16x16x32_bf16 v[92:95], v[140:143], v[216:219], v[92:95]
	v_mfma_f32_16x16x32_bf16 v[80:83], v[132:135], v[224:227], v[80:83]
	v_mfma_f32_16x16x32_bf16 v[76:79], v[140:143], v[224:227], v[76:79]
	v_mfma_f32_16x16x32_bf16 v[128:131], v[136:139], v[204:207], v[128:131]
	v_mfma_f32_16x16x32_bf16 v[124:127], v[178:181], v[204:207], v[124:127]
	v_mfma_f32_16x16x32_bf16 v[112:115], v[136:139], v[212:215], v[112:115]
	v_mfma_f32_16x16x32_bf16 v[108:111], v[178:181], v[212:215], v[108:111]
	v_mfma_f32_16x16x32_bf16 v[96:99], v[136:139], v[220:223], v[96:99]
	v_mfma_f32_16x16x32_bf16 v[92:95], v[178:181], v[220:223], v[92:95]
	v_mfma_f32_16x16x32_bf16 v[80:83], v[136:139], v[228:231], v[80:83]
	v_mfma_f32_16x16x32_bf16 v[76:79], v[178:181], v[228:231], v[76:79]
	s_setprio 0
	s_setprio 1
	v_mfma_f32_16x16x32_bf16 v[120:123], v[182:185], v[200:203], v[120:123]
	v_mfma_f32_16x16x32_bf16 v[116:119], v[192:195], v[200:203], v[116:119]
	v_mfma_f32_16x16x32_bf16 v[104:107], v[182:185], v[208:211], v[104:107]
	v_mfma_f32_16x16x32_bf16 v[100:103], v[192:195], v[208:211], v[100:103]
	v_mfma_f32_16x16x32_bf16 v[88:91], v[182:185], v[216:219], v[88:91]
	v_mfma_f32_16x16x32_bf16 v[84:87], v[192:195], v[216:219], v[84:87]
	v_mfma_f32_16x16x32_bf16 v[72:75], v[182:185], v[224:227], v[72:75]
	v_mfma_f32_16x16x32_bf16 v[68:71], v[192:195], v[224:227], v[68:71]
	v_mfma_f32_16x16x32_bf16 v[120:123], v[188:191], v[204:207], v[120:123]
	v_mfma_f32_16x16x32_bf16 v[116:119], v[196:199], v[204:207], v[116:119]
	v_mfma_f32_16x16x32_bf16 v[104:107], v[188:191], v[212:215], v[104:107]
	v_mfma_f32_16x16x32_bf16 v[100:103], v[196:199], v[212:215], v[100:103]
	v_mfma_f32_16x16x32_bf16 v[88:91], v[188:191], v[220:223], v[88:91]
	v_mfma_f32_16x16x32_bf16 v[84:87], v[196:199], v[220:223], v[84:87]
	v_mfma_f32_16x16x32_bf16 v[72:75], v[188:191], v[228:231], v[72:75]
	v_mfma_f32_16x16x32_bf16 v[68:71], v[196:199], v[228:231], v[68:71]
	s_setprio 0
	s_barrier
	s_add_i32 s75, s79, s68
	v_lshl_add_u64 v[232:233], s[64:65], 0, v[148:149]
	s_mov_b32 m0, s75
	ds_read_b128 v[200:203], v174 offset:16384
	ds_read_b128 v[204:207], v174 offset:17408
	ds_read_b128 v[208:211], v174 offset:18432
	ds_read_b128 v[212:215], v174 offset:19456
	ds_read_b128 v[216:219], v174 offset:20480
	ds_read_b128 v[220:223], v174 offset:21504
	ds_read_b128 v[224:227], v174 offset:22528
	ds_read_b128 v[228:231], v174 offset:23552
	global_load_lds_dwordx4 v[232:233], off
	s_add_i32 m0, s75, 0x2000
	s_add_u32 s92, s64, 0xa0000
	v_lshl_add_u64 v[234:235], s[64:65], 0, v[144:145]
	s_addc_u32 s93, s65, 0
	s_add_i32 s75, s80, s68
	global_load_lds_dwordx4 v[234:235], off
	v_lshl_add_u64 v[2:3], s[92:93], 0, v[148:149]
	s_mov_b32 m0, s75
	v_lshl_add_u64 v[236:237], s[66:67], 0, v[150:151]
	global_load_lds_dwordx4 v[2:3], off
	v_lshl_add_u64 v[2:3], s[92:93], 0, v[144:145]
	s_add_i32 m0, s75, 0x2000
	v_lshl_add_u64 v[238:239], s[66:67], 0, v[146:147]
	global_load_lds_dwordx4 v[2:3], off
	s_mov_b32 m0, s69
	s_nop 0
	global_load_lds_dwordx4 v[236:237], off
	s_mov_b32 m0, s70
	s_nop 0
	global_load_lds_dwordx4 v[238:239], off
	s_waitcnt vmcnt(8)
	s_waitcnt lgkmcnt(0)
	s_barrier
	s_setprio 1
	s_waitcnt lgkmcnt(0)
	v_mfma_f32_16x16x32_bf16 v[64:67], v[132:135], v[200:203], v[64:67]
	v_mfma_f32_16x16x32_bf16 v[60:63], v[140:143], v[200:203], v[60:63]
	v_mfma_f32_16x16x32_bf16 v[48:51], v[132:135], v[208:211], v[48:51]
	v_mfma_f32_16x16x32_bf16 v[44:47], v[140:143], v[208:211], v[44:47]
	v_mfma_f32_16x16x32_bf16 v[32:35], v[132:135], v[216:219], v[32:35]
	v_mfma_f32_16x16x32_bf16 v[28:31], v[140:143], v[216:219], v[28:31]
	v_mfma_f32_16x16x32_bf16 v[16:19], v[132:135], v[224:227], v[16:19]
	v_mfma_f32_16x16x32_bf16 v[12:15], v[140:143], v[224:227], v[12:15]
	v_mfma_f32_16x16x32_bf16 v[64:67], v[136:139], v[204:207], v[64:67]
	v_mfma_f32_16x16x32_bf16 v[60:63], v[178:181], v[204:207], v[60:63]
	v_mfma_f32_16x16x32_bf16 v[48:51], v[136:139], v[212:215], v[48:51]
	v_mfma_f32_16x16x32_bf16 v[44:47], v[178:181], v[212:215], v[44:47]
	v_mfma_f32_16x16x32_bf16 v[32:35], v[136:139], v[220:223], v[32:35]
	v_mfma_f32_16x16x32_bf16 v[28:31], v[178:181], v[220:223], v[28:31]
	v_mfma_f32_16x16x32_bf16 v[16:19], v[136:139], v[228:231], v[16:19]
	v_mfma_f32_16x16x32_bf16 v[12:15], v[178:181], v[228:231], v[12:15]
	s_setprio 0
	s_setprio 1
	v_mfma_f32_16x16x32_bf16 v[56:59], v[182:185], v[200:203], v[56:59]
	v_mfma_f32_16x16x32_bf16 v[52:55], v[192:195], v[200:203], v[52:55]
	v_mfma_f32_16x16x32_bf16 v[40:43], v[182:185], v[208:211], v[40:43]
	v_mfma_f32_16x16x32_bf16 v[36:39], v[192:195], v[208:211], v[36:39]
	v_mfma_f32_16x16x32_bf16 v[24:27], v[182:185], v[216:219], v[24:27]
	v_mfma_f32_16x16x32_bf16 v[20:23], v[192:195], v[216:219], v[20:23]
	v_mfma_f32_16x16x32_bf16 v[8:11], v[182:185], v[224:227], v[8:11]
	v_mfma_f32_16x16x32_bf16 v[2:5], v[192:195], v[224:227], v[4:7]
	v_mfma_f32_16x16x32_bf16 v[56:59], v[188:191], v[204:207], v[56:59]
	v_mfma_f32_16x16x32_bf16 v[52:55], v[196:199], v[204:207], v[52:55]
	v_mfma_f32_16x16x32_bf16 v[40:43], v[188:191], v[212:215], v[40:43]
	v_mfma_f32_16x16x32_bf16 v[36:39], v[196:199], v[212:215], v[36:39]
	v_mfma_f32_16x16x32_bf16 v[24:27], v[188:191], v[220:223], v[24:27]
	v_mfma_f32_16x16x32_bf16 v[20:23], v[196:199], v[220:223], v[20:23]
	v_mfma_f32_16x16x32_bf16 v[8:11], v[188:191], v[228:231], v[8:11]
	v_mfma_f32_16x16x32_bf16 v[2:5], v[196:199], v[228:231], v[2:5]
	s_setprio 0
	s_barrier
	s_add_i32 s75, 0, 0x18000
	v_add_u32_e32 v1, s75, v173
	s_add_i32 s91, 0, 0x1c000
	ds_read_b128 v[132:135], v1
	ds_read_b128 v[136:139], v1 offset:1024
	ds_read_b128 v[140:143], v1 offset:2048
	ds_read_b128 v[178:181], v1 offset:3072
	v_add_u32_e32 v1, s91, v173
	ds_read_b128 v[182:185], v1
	ds_read_b128 v[188:191], v1 offset:1024
	ds_read_b128 v[192:195], v1 offset:2048
	ds_read_b128 v[196:199], v1 offset:3072
	s_add_u32 s66, s66, 0xa0000
	s_addc_u32 s67, s67, 0
	s_mov_b32 m0, s71
	v_lshl_add_u64 v[6:7], s[66:67], 0, v[150:151]
	ds_read_b128 v[200:203], v174 offset:32768
	ds_read_b128 v[204:207], v174 offset:33792
	ds_read_b128 v[208:211], v174 offset:34816
	ds_read_b128 v[212:215], v174 offset:35840
	ds_read_b128 v[216:219], v174 offset:36864
	ds_read_b128 v[220:223], v174 offset:37888
	ds_read_b128 v[224:227], v174 offset:38912
	ds_read_b128 v[228:231], v174 offset:39936
	global_load_lds_dwordx4 v[6:7], off
	v_lshl_add_u64 v[6:7], s[66:67], 0, v[146:147]
	s_mov_b32 m0, s72
	s_nop 0
	global_load_lds_dwordx4 v[6:7], off
	s_waitcnt vmcnt(8)
	s_waitcnt lgkmcnt(0)
	s_barrier
	s_setprio 1
	s_waitcnt lgkmcnt(0)
	v_mfma_f32_16x16x32_bf16 v[128:131], v[132:135], v[200:203], v[128:131]
	v_mfma_f32_16x16x32_bf16 v[124:127], v[140:143], v[200:203], v[124:127]
	v_mfma_f32_16x16x32_bf16 v[112:115], v[132:135], v[208:211], v[112:115]
	v_mfma_f32_16x16x32_bf16 v[108:111], v[140:143], v[208:211], v[108:111]
	v_mfma_f32_16x16x32_bf16 v[96:99], v[132:135], v[216:219], v[96:99]
	v_mfma_f32_16x16x32_bf16 v[92:95], v[140:143], v[216:219], v[92:95]
	v_mfma_f32_16x16x32_bf16 v[80:83], v[132:135], v[224:227], v[80:83]
	v_mfma_f32_16x16x32_bf16 v[76:79], v[140:143], v[224:227], v[76:79]
	v_mfma_f32_16x16x32_bf16 v[128:131], v[136:139], v[204:207], v[128:131]
	v_mfma_f32_16x16x32_bf16 v[124:127], v[178:181], v[204:207], v[124:127]
	v_mfma_f32_16x16x32_bf16 v[112:115], v[136:139], v[212:215], v[112:115]
	v_mfma_f32_16x16x32_bf16 v[108:111], v[178:181], v[212:215], v[108:111]
	v_mfma_f32_16x16x32_bf16 v[96:99], v[136:139], v[220:223], v[96:99]
	v_mfma_f32_16x16x32_bf16 v[92:95], v[178:181], v[220:223], v[92:95]
	v_mfma_f32_16x16x32_bf16 v[80:83], v[136:139], v[228:231], v[80:83]
	v_mfma_f32_16x16x32_bf16 v[76:79], v[178:181], v[228:231], v[76:79]
	s_setprio 0
	s_setprio 1
	v_mfma_f32_16x16x32_bf16 v[120:123], v[182:185], v[200:203], v[120:123]
	v_mfma_f32_16x16x32_bf16 v[116:119], v[192:195], v[200:203], v[116:119]
	v_mfma_f32_16x16x32_bf16 v[104:107], v[182:185], v[208:211], v[104:107]
	v_mfma_f32_16x16x32_bf16 v[100:103], v[192:195], v[208:211], v[100:103]
	v_mfma_f32_16x16x32_bf16 v[88:91], v[182:185], v[216:219], v[88:91]
	v_mfma_f32_16x16x32_bf16 v[84:87], v[192:195], v[216:219], v[84:87]
	v_mfma_f32_16x16x32_bf16 v[72:75], v[182:185], v[224:227], v[72:75]
	v_mfma_f32_16x16x32_bf16 v[68:71], v[192:195], v[224:227], v[68:71]
	v_mfma_f32_16x16x32_bf16 v[120:123], v[188:191], v[204:207], v[120:123]
	v_mfma_f32_16x16x32_bf16 v[116:119], v[196:199], v[204:207], v[116:119]
	v_mfma_f32_16x16x32_bf16 v[104:107], v[188:191], v[212:215], v[104:107]
	v_mfma_f32_16x16x32_bf16 v[100:103], v[196:199], v[212:215], v[100:103]
	v_mfma_f32_16x16x32_bf16 v[88:91], v[188:191], v[220:223], v[88:91]
	v_mfma_f32_16x16x32_bf16 v[84:87], v[196:199], v[220:223], v[84:87]
	v_mfma_f32_16x16x32_bf16 v[72:75], v[188:191], v[228:231], v[72:75]
	v_mfma_f32_16x16x32_bf16 v[68:71], v[196:199], v[228:231], v[68:71]
	s_setprio 0
	s_barrier
	s_add_i32 s66, s75, s68
	v_lshl_add_u64 v[6:7], v[232:233], 0, s[14:15]
	s_mov_b32 m0, s66
	ds_read_b128 v[200:203], v174 offset:49152
	ds_read_b128 v[204:207], v174 offset:50176
	ds_read_b128 v[208:211], v174 offset:51200
	ds_read_b128 v[212:215], v174 offset:52224
	ds_read_b128 v[216:219], v174 offset:53248
	ds_read_b128 v[220:223], v174 offset:54272
	ds_read_b128 v[224:227], v174 offset:55296
	ds_read_b128 v[228:231], v174 offset:56320
	global_load_lds_dwordx4 v[6:7], off
	s_add_i32 m0, s66, 0x2000
	s_add_u32 s64, s64, 0xa0080
	v_lshl_add_u64 v[6:7], v[234:235], 0, s[14:15]
	s_addc_u32 s65, s65, 0
	s_add_i32 s66, s91, s68
	global_load_lds_dwordx4 v[6:7], off
	v_lshl_add_u64 v[6:7], s[64:65], 0, v[148:149]
	s_mov_b32 m0, s66
	s_nop 0
	global_load_lds_dwordx4 v[6:7], off
	v_lshl_add_u64 v[6:7], s[64:65], 0, v[144:145]
	s_add_i32 m0, s66, 0x2000
	s_nop 0
	global_load_lds_dwordx4 v[6:7], off
	v_lshl_add_u64 v[6:7], v[236:237], 0, s[14:15]
	s_mov_b32 m0, s73
	s_nop 0
	global_load_lds_dwordx4 v[6:7], off
	v_lshl_add_u64 v[6:7], v[238:239], 0, s[14:15]
	s_mov_b32 m0, s76
	s_nop 0
	global_load_lds_dwordx4 v[6:7], off
	s_waitcnt vmcnt(8)
	s_waitcnt lgkmcnt(0)
	s_barrier
	s_setprio 1
	s_waitcnt lgkmcnt(0)
	v_mfma_f32_16x16x32_bf16 v[64:67], v[132:135], v[200:203], v[64:67]
	v_mfma_f32_16x16x32_bf16 v[60:63], v[140:143], v[200:203], v[60:63]
	v_mfma_f32_16x16x32_bf16 v[48:51], v[132:135], v[208:211], v[48:51]
	v_mfma_f32_16x16x32_bf16 v[44:47], v[140:143], v[208:211], v[44:47]
	v_mfma_f32_16x16x32_bf16 v[32:35], v[132:135], v[216:219], v[32:35]
	v_mfma_f32_16x16x32_bf16 v[28:31], v[140:143], v[216:219], v[28:31]
	v_mfma_f32_16x16x32_bf16 v[16:19], v[132:135], v[224:227], v[16:19]
	v_mfma_f32_16x16x32_bf16 v[12:15], v[140:143], v[224:227], v[12:15]
	v_mfma_f32_16x16x32_bf16 v[64:67], v[136:139], v[204:207], v[64:67]
	v_mfma_f32_16x16x32_bf16 v[60:63], v[178:181], v[204:207], v[60:63]
	v_mfma_f32_16x16x32_bf16 v[48:51], v[136:139], v[212:215], v[48:51]
	v_mfma_f32_16x16x32_bf16 v[44:47], v[178:181], v[212:215], v[44:47]
	v_mfma_f32_16x16x32_bf16 v[32:35], v[136:139], v[220:223], v[32:35]
	v_mfma_f32_16x16x32_bf16 v[28:31], v[178:181], v[220:223], v[28:31]
	v_mfma_f32_16x16x32_bf16 v[16:19], v[136:139], v[228:231], v[16:19]
	v_mfma_f32_16x16x32_bf16 v[12:15], v[178:181], v[228:231], v[12:15]
	s_setprio 0
	s_setprio 1
	v_mfma_f32_16x16x32_bf16 v[56:59], v[182:185], v[200:203], v[56:59]
	v_mfma_f32_16x16x32_bf16 v[52:55], v[192:195], v[200:203], v[52:55]
	v_mfma_f32_16x16x32_bf16 v[40:43], v[182:185], v[208:211], v[40:43]
	v_mfma_f32_16x16x32_bf16 v[36:39], v[192:195], v[208:211], v[36:39]
	v_mfma_f32_16x16x32_bf16 v[24:27], v[182:185], v[216:219], v[24:27]
	v_mfma_f32_16x16x32_bf16 v[20:23], v[192:195], v[216:219], v[20:23]
	v_mfma_f32_16x16x32_bf16 v[6:9], v[182:185], v[224:227], v[8:11]
	v_mfma_f32_16x16x32_bf16 v[2:5], v[192:195], v[224:227], v[2:5]
	v_mfma_f32_16x16x32_bf16 v[56:59], v[188:191], v[204:207], v[56:59]
	v_mfma_f32_16x16x32_bf16 v[52:55], v[196:199], v[204:207], v[52:55]
	v_mfma_f32_16x16x32_bf16 v[40:43], v[188:191], v[212:215], v[40:43]
	v_mfma_f32_16x16x32_bf16 v[36:39], v[196:199], v[212:215], v[36:39]
	v_mfma_f32_16x16x32_bf16 v[24:27], v[188:191], v[220:223], v[24:27]
	v_mfma_f32_16x16x32_bf16 v[20:23], v[196:199], v[220:223], v[20:23]
	v_mfma_f32_16x16x32_bf16 v[8:11], v[188:191], v[228:231], v[6:9]
	v_mfma_f32_16x16x32_bf16 v[4:7], v[196:199], v[228:231], v[2:5]
	s_setprio 0
	s_and_b64 vcc, exec, s[18:19]
	s_cbranch_vccnz .Lhk_skipB
	s_and_b64 vcc, exec, s[62:63]
	s_cbranch_vccnz .Lhk_skipB
	s_cmp_eq_u32 s2, 16
	s_cbranch_scc1 .Lhk_doB
	s_cmp_eq_u32 s2, 24
	s_cbranch_scc0 .Lhk_skipB
.Lhk_doB:
	s_cmp_eq_u32 s2, 16
	s_cselect_b32 s99, 0, 1
	s_add_i32 s99, s98, s99
	s_lshl_b32 s99, s99, 17
	s_add_u32 s100, s38, 0xba00000
	s_addc_u32 s101, s39, 0
	s_add_u32 s100, s100, s99
	s_addc_u32 s101, s101, 0
	v_lshrrev_b32_e32 v2, 6, v175
	v_mul_u32_u24_e32 v2, 0x3c00, v2
	v_lshl_add_u32 v2, v175, 4, v2
	v_mov_b32_e32 v3, 0
	v_lshl_add_u64 v[2:3], s[100:101], 0, v[2:3]
	s_mov_b64 s[100:101], 0x20000
	v_lshl_add_u64 v[254:255], v[2:3], 0, s[100:101]
	global_load_dwordx4 v[132:135], v[2:3], off
	global_load_dwordx4 v[136:139], v[2:3], off offset:1024
	global_load_dwordx4 v[140:143], v[254:255], off
	global_load_dwordx4 v[188:191], v[254:255], off offset:1024
	v_lshl_add_u64 v[2:3], v[2:3], 0, s[20:21]
	v_lshl_add_u64 v[254:255], v[254:255], 0, s[20:21]
	global_load_dwordx4 v[192:195], v[2:3], off
	global_load_dwordx4 v[196:199], v[2:3], off offset:1024
	global_load_dwordx4 v[200:203], v[254:255], off
	global_load_dwordx4 v[204:207], v[254:255], off offset:1024
	v_lshl_add_u64 v[2:3], v[2:3], 0, s[20:21]
	v_lshl_add_u64 v[254:255], v[254:255], 0, s[20:21]
	global_load_dwordx4 v[208:211], v[2:3], off
	global_load_dwordx4 v[212:215], v[2:3], off offset:1024
	global_load_dwordx4 v[216:219], v[254:255], off
	global_load_dwordx4 v[220:223], v[254:255], off offset:1024
	v_lshl_add_u64 v[2:3], v[2:3], 0, s[20:21]
	v_lshl_add_u64 v[254:255], v[254:255], 0, s[20:21]
	global_load_dwordx4 v[224:227], v[2:3], off
	global_load_dwordx4 v[228:231], v[2:3], off offset:1024
	global_load_dwordx4 v[232:235], v[254:255], off
	global_load_dwordx4 v[236:239], v[254:255], off offset:1024
	v_lshl_add_u64 v[2:3], v[2:3], 0, s[20:21]
	v_lshl_add_u64 v[254:255], v[254:255], 0, s[20:21]
	s_waitcnt vmcnt(12)
	v_lshlrev_b32_e32 v178, 16, v140
	v_and_b32_e32 v179, 0xffff0000, v140
	v_lshlrev_b32_e32 v180, 16, v141
	v_and_b32_e32 v181, 0xffff0000, v141
	v_lshlrev_b32_e32 v182, 16, v142
	v_and_b32_e32 v183, 0xffff0000, v142
	v_lshlrev_b32_e32 v184, 16, v143
	v_and_b32_e32 v185, 0xffff0000, v143
	v_rcp_f32_e32 v178, v178
	v_rcp_f32_e32 v179, v179
	v_rcp_f32_e32 v180, v180
	v_rcp_f32_e32 v181, v181
	v_rcp_f32_e32 v182, v182
	v_rcp_f32_e32 v183, v183
	v_rcp_f32_e32 v184, v184
	v_rcp_f32_e32 v185, v185
	v_lshlrev_b32_e32 v140, 16, v132
	v_and_b32_e32 v141, 0xffff0000, v132
	v_lshlrev_b32_e32 v142, 16, v133
	v_and_b32_e32 v143, 0xffff0000, v133
	v_lshlrev_b32_e32 v132, 16, v134
	v_and_b32_e32 v133, 0xffff0000, v134
	v_lshlrev_b32_e32 v134, 16, v135
	v_and_b32_e32 v135, 0xffff0000, v135
	v_pk_mul_f32 v[178:179], v[178:179], v[140:141]
	v_pk_mul_f32 v[180:181], v[180:181], v[142:143]
	v_pk_mul_f32 v[182:183], v[182:183], v[132:133]
	v_pk_mul_f32 v[184:185], v[184:185], v[134:135]
	v_pk_mul_f32 v[128:129], v[128:129], v[178:179]
	v_pk_mul_f32 v[130:131], v[130:131], v[180:181]
	v_pk_mul_f32 v[124:125], v[124:125], v[182:183]
	v_pk_mul_f32 v[126:127], v[126:127], v[184:185]
	v_lshlrev_b32_e32 v246, 16, v188
	v_and_b32_e32 v247, 0xffff0000, v188
	v_lshlrev_b32_e32 v248, 16, v189
	v_and_b32_e32 v249, 0xffff0000, v189
	v_lshlrev_b32_e32 v250, 16, v190
	v_and_b32_e32 v251, 0xffff0000, v190
	v_lshlrev_b32_e32 v252, 16, v191
	v_and_b32_e32 v253, 0xffff0000, v191
	v_rcp_f32_e32 v246, v246
	v_rcp_f32_e32 v247, v247
	v_rcp_f32_e32 v248, v248
	v_rcp_f32_e32 v249, v249
	v_rcp_f32_e32 v250, v250
	v_rcp_f32_e32 v251, v251
	v_rcp_f32_e32 v252, v252
	v_rcp_f32_e32 v253, v253
	v_lshlrev_b32_e32 v188, 16, v136
	v_and_b32_e32 v189, 0xffff0000, v136
	v_lshlrev_b32_e32 v190, 16, v137
	v_and_b32_e32 v191, 0xffff0000, v137
	v_lshlrev_b32_e32 v136, 16, v138
	v_and_b32_e32 v137, 0xffff0000, v138
	v_lshlrev_b32_e32 v138, 16, v139
	v_and_b32_e32 v139, 0xffff0000, v139
	v_pk_mul_f32 v[246:247], v[246:247], v[188:189]
	v_pk_mul_f32 v[248:249], v[248:249], v[190:191]
	v_pk_mul_f32 v[250:251], v[250:251], v[136:137]
	v_pk_mul_f32 v[252:253], v[252:253], v[138:139]
	v_pk_mul_f32 v[120:121], v[120:121], v[246:247]
	v_pk_mul_f32 v[122:123], v[122:123], v[248:249]
	v_pk_mul_f32 v[116:117], v[116:117], v[250:251]
	v_pk_mul_f32 v[118:119], v[118:119], v[252:253]
	global_load_dwordx4 v[132:135], v[2:3], off
	global_load_dwordx4 v[136:139], v[2:3], off offset:1024
	global_load_dwordx4 v[140:143], v[254:255], off
	global_load_dwordx4 v[188:191], v[254:255], off offset:1024
	v_lshl_add_u64 v[2:3], v[2:3], 0, s[20:21]
	v_lshl_add_u64 v[254:255], v[254:255], 0, s[20:21]
	s_waitcnt vmcnt(12)
	v_lshlrev_b32_e32 v178, 16, v200
	v_and_b32_e32 v179, 0xffff0000, v200
	v_lshlrev_b32_e32 v180, 16, v201
	v_and_b32_e32 v181, 0xffff0000, v201
	v_lshlrev_b32_e32 v182, 16, v202
	v_and_b32_e32 v183, 0xffff0000, v202
	v_lshlrev_b32_e32 v184, 16, v203
	v_and_b32_e32 v185, 0xffff0000, v203
	v_rcp_f32_e32 v178, v178
	v_rcp_f32_e32 v179, v179
	v_rcp_f32_e32 v180, v180
	v_rcp_f32_e32 v181, v181
	v_rcp_f32_e32 v182, v182
	v_rcp_f32_e32 v183, v183
	v_rcp_f32_e32 v184, v184
	v_rcp_f32_e32 v185, v185
	v_lshlrev_b32_e32 v200, 16, v192
	v_and_b32_e32 v201, 0xffff0000, v192
	v_lshlrev_b32_e32 v202, 16, v193
	v_and_b32_e32 v203, 0xffff0000, v193
	v_lshlrev_b32_e32 v192, 16, v194
	v_and_b32_e32 v193, 0xffff0000, v194
	v_lshlrev_b32_e32 v194, 16, v195
	v_and_b32_e32 v195, 0xffff0000, v195
	v_pk_mul_f32 v[178:179], v[178:179], v[200:201]
	v_pk_mul_f32 v[180:181], v[180:181], v[202:203]
	v_pk_mul_f32 v[182:183], v[182:183], v[192:193]
	v_pk_mul_f32 v[184:185], v[184:185], v[194:195]
	v_pk_mul_f32 v[112:113], v[112:113], v[178:179]
	v_pk_mul_f32 v[114:115], v[114:115], v[180:181]
	v_pk_mul_f32 v[108:109], v[108:109], v[182:183]
	v_pk_mul_f32 v[110:111], v[110:111], v[184:185]
	v_lshlrev_b32_e32 v246, 16, v204
	v_and_b32_e32 v247, 0xffff0000, v204
	v_lshlrev_b32_e32 v248, 16, v205
	v_and_b32_e32 v249, 0xffff0000, v205
	v_lshlrev_b32_e32 v250, 16, v206
	v_and_b32_e32 v251, 0xffff0000, v206
	v_lshlrev_b32_e32 v252, 16, v207
	v_and_b32_e32 v253, 0xffff0000, v207
	v_rcp_f32_e32 v246, v246
	v_rcp_f32_e32 v247, v247
	v_rcp_f32_e32 v248, v248
	v_rcp_f32_e32 v249, v249
	v_rcp_f32_e32 v250, v250
	v_rcp_f32_e32 v251, v251
	v_rcp_f32_e32 v252, v252
	v_rcp_f32_e32 v253, v253
	v_lshlrev_b32_e32 v204, 16, v196
	v_and_b32_e32 v205, 0xffff0000, v196
	v_lshlrev_b32_e32 v206, 16, v197
	v_and_b32_e32 v207, 0xffff0000, v197
	v_lshlrev_b32_e32 v196, 16, v198
	v_and_b32_e32 v197, 0xffff0000, v198
	v_lshlrev_b32_e32 v198, 16, v199
	v_and_b32_e32 v199, 0xffff0000, v199
	v_pk_mul_f32 v[246:247], v[246:247], v[204:205]
	v_pk_mul_f32 v[248:249], v[248:249], v[206:207]
	v_pk_mul_f32 v[250:251], v[250:251], v[196:197]
	v_pk_mul_f32 v[252:253], v[252:253], v[198:199]
	v_pk_mul_f32 v[104:105], v[104:105], v[246:247]
	v_pk_mul_f32 v[106:107], v[106:107], v[248:249]
	v_pk_mul_f32 v[100:101], v[100:101], v[250:251]
	v_pk_mul_f32 v[102:103], v[102:103], v[252:253]
	global_load_dwordx4 v[192:195], v[2:3], off
	global_load_dwordx4 v[196:199], v[2:3], off offset:1024
	global_load_dwordx4 v[200:203], v[254:255], off
	global_load_dwordx4 v[204:207], v[254:255], off offset:1024
	v_lshl_add_u64 v[2:3], v[2:3], 0, s[20:21]
	v_lshl_add_u64 v[254:255], v[254:255], 0, s[20:21]
	s_waitcnt vmcnt(12)
	v_lshlrev_b32_e32 v178, 16, v216
	v_and_b32_e32 v179, 0xffff0000, v216
	v_lshlrev_b32_e32 v180, 16, v217
	v_and_b32_e32 v181, 0xffff0000, v217
	v_lshlrev_b32_e32 v182, 16, v218
	v_and_b32_e32 v183, 0xffff0000, v218
	v_lshlrev_b32_e32 v184, 16, v219
	v_and_b32_e32 v185, 0xffff0000, v219
	v_rcp_f32_e32 v178, v178
	v_rcp_f32_e32 v179, v179
	v_rcp_f32_e32 v180, v180
	v_rcp_f32_e32 v181, v181
	v_rcp_f32_e32 v182, v182
	v_rcp_f32_e32 v183, v183
	v_rcp_f32_e32 v184, v184
	v_rcp_f32_e32 v185, v185
	v_lshlrev_b32_e32 v216, 16, v208
	v_and_b32_e32 v217, 0xffff0000, v208
	v_lshlrev_b32_e32 v218, 16, v209
	v_and_b32_e32 v219, 0xffff0000, v209
	v_lshlrev_b32_e32 v208, 16, v210
	v_and_b32_e32 v209, 0xffff0000, v210
	v_lshlrev_b32_e32 v210, 16, v211
	v_and_b32_e32 v211, 0xffff0000, v211
	v_pk_mul_f32 v[178:179], v[178:179], v[216:217]
	v_pk_mul_f32 v[180:181], v[180:181], v[218:219]
	v_pk_mul_f32 v[182:183], v[182:183], v[208:209]
	v_pk_mul_f32 v[184:185], v[184:185], v[210:211]
	v_pk_mul_f32 v[96:97], v[96:97], v[178:179]
	v_pk_mul_f32 v[98:99], v[98:99], v[180:181]
	v_pk_mul_f32 v[92:93], v[92:93], v[182:183]
	v_pk_mul_f32 v[94:95], v[94:95], v[184:185]
	v_lshlrev_b32_e32 v246, 16, v220
	v_and_b32_e32 v247, 0xffff0000, v220
	v_lshlrev_b32_e32 v248, 16, v221
	v_and_b32_e32 v249, 0xffff0000, v221
	v_lshlrev_b32_e32 v250, 16, v222
	v_and_b32_e32 v251, 0xffff0000, v222
	v_lshlrev_b32_e32 v252, 16, v223
	v_and_b32_e32 v253, 0xffff0000, v223
	v_rcp_f32_e32 v246, v246
	v_rcp_f32_e32 v247, v247
	v_rcp_f32_e32 v248, v248
	v_rcp_f32_e32 v249, v249
	v_rcp_f32_e32 v250, v250
	v_rcp_f32_e32 v251, v251
	v_rcp_f32_e32 v252, v252
	v_rcp_f32_e32 v253, v253
	v_lshlrev_b32_e32 v220, 16, v212
	v_and_b32_e32 v221, 0xffff0000, v212
	v_lshlrev_b32_e32 v222, 16, v213
	v_and_b32_e32 v223, 0xffff0000, v213
	v_lshlrev_b32_e32 v212, 16, v214
	v_and_b32_e32 v213, 0xffff0000, v214
	v_lshlrev_b32_e32 v214, 16, v215
	v_and_b32_e32 v215, 0xffff0000, v215
	v_pk_mul_f32 v[246:247], v[246:247], v[220:221]
	v_pk_mul_f32 v[248:249], v[248:249], v[222:223]
	v_pk_mul_f32 v[250:251], v[250:251], v[212:213]
	v_pk_mul_f32 v[252:253], v[252:253], v[214:215]
	v_pk_mul_f32 v[88:89], v[88:89], v[246:247]
	v_pk_mul_f32 v[90:91], v[90:91], v[248:249]
	v_pk_mul_f32 v[84:85], v[84:85], v[250:251]
	v_pk_mul_f32 v[86:87], v[86:87], v[252:253]
	global_load_dwordx4 v[208:211], v[2:3], off
	global_load_dwordx4 v[212:215], v[2:3], off offset:1024
	global_load_dwordx4 v[216:219], v[254:255], off
	global_load_dwordx4 v[220:223], v[254:255], off offset:1024
	v_lshl_add_u64 v[2:3], v[2:3], 0, s[20:21]
	v_lshl_add_u64 v[254:255], v[254:255], 0, s[20:21]
	s_waitcnt vmcnt(12)
	v_lshlrev_b32_e32 v178, 16, v232
	v_and_b32_e32 v179, 0xffff0000, v232
	v_lshlrev_b32_e32 v180, 16, v233
	v_and_b32_e32 v181, 0xffff0000, v233
	v_lshlrev_b32_e32 v182, 16, v234
	v_and_b32_e32 v183, 0xffff0000, v234
	v_lshlrev_b32_e32 v184, 16, v235
	v_and_b32_e32 v185, 0xffff0000, v235
	v_rcp_f32_e32 v178, v178
	v_rcp_f32_e32 v179, v179
	v_rcp_f32_e32 v180, v180
	v_rcp_f32_e32 v181, v181
	v_rcp_f32_e32 v182, v182
	v_rcp_f32_e32 v183, v183
	v_rcp_f32_e32 v184, v184
	v_rcp_f32_e32 v185, v185
	v_lshlrev_b32_e32 v232, 16, v224
	v_and_b32_e32 v233, 0xffff0000, v224
	v_lshlrev_b32_e32 v234, 16, v225
	v_and_b32_e32 v235, 0xffff0000, v225
	v_lshlrev_b32_e32 v224, 16, v226
	v_and_b32_e32 v225, 0xffff0000, v226
	v_lshlrev_b32_e32 v226, 16, v227
	v_and_b32_e32 v227, 0xffff0000, v227
	v_pk_mul_f32 v[178:179], v[178:179], v[232:233]
	v_pk_mul_f32 v[180:181], v[180:181], v[234:235]
	v_pk_mul_f32 v[182:183], v[182:183], v[224:225]
	v_pk_mul_f32 v[184:185], v[184:185], v[226:227]
	v_pk_mul_f32 v[80:81], v[80:81], v[178:179]
	v_pk_mul_f32 v[82:83], v[82:83], v[180:181]
	v_pk_mul_f32 v[76:77], v[76:77], v[182:183]
	v_pk_mul_f32 v[78:79], v[78:79], v[184:185]
	v_lshlrev_b32_e32 v246, 16, v236
	v_and_b32_e32 v247, 0xffff0000, v236
	v_lshlrev_b32_e32 v248, 16, v237
	v_and_b32_e32 v249, 0xffff0000, v237
	v_lshlrev_b32_e32 v250, 16, v238
	v_and_b32_e32 v251, 0xffff0000, v238
	v_lshlrev_b32_e32 v252, 16, v239
	v_and_b32_e32 v253, 0xffff0000, v239
	v_rcp_f32_e32 v246, v246
	v_rcp_f32_e32 v247, v247
	v_rcp_f32_e32 v248, v248
	v_rcp_f32_e32 v249, v249
	v_rcp_f32_e32 v250, v250
	v_rcp_f32_e32 v251, v251
	v_rcp_f32_e32 v252, v252
	v_rcp_f32_e32 v253, v253
	v_lshlrev_b32_e32 v236, 16, v228
	v_and_b32_e32 v237, 0xffff0000, v228
	v_lshlrev_b32_e32 v238, 16, v229
	v_and_b32_e32 v239, 0xffff0000, v229
	v_lshlrev_b32_e32 v228, 16, v230
	v_and_b32_e32 v229, 0xffff0000, v230
	v_lshlrev_b32_e32 v230, 16, v231
	v_and_b32_e32 v231, 0xffff0000, v231
	v_pk_mul_f32 v[246:247], v[246:247], v[236:237]
	v_pk_mul_f32 v[248:249], v[248:249], v[238:239]
	v_pk_mul_f32 v[250:251], v[250:251], v[228:229]
	v_pk_mul_f32 v[252:253], v[252:253], v[230:231]
	v_pk_mul_f32 v[72:73], v[72:73], v[246:247]
	v_pk_mul_f32 v[74:75], v[74:75], v[248:249]
	v_pk_mul_f32 v[68:69], v[68:69], v[250:251]
	v_pk_mul_f32 v[70:71], v[70:71], v[252:253]
	global_load_dwordx4 v[224:227], v[2:3], off
	global_load_dwordx4 v[228:231], v[2:3], off offset:1024
	global_load_dwordx4 v[232:235], v[254:255], off
	global_load_dwordx4 v[236:239], v[254:255], off offset:1024
	s_waitcnt vmcnt(12)
	v_lshlrev_b32_e32 v178, 16, v140
	v_and_b32_e32 v179, 0xffff0000, v140
	v_lshlrev_b32_e32 v180, 16, v141
	v_and_b32_e32 v181, 0xffff0000, v141
	v_lshlrev_b32_e32 v182, 16, v142
	v_and_b32_e32 v183, 0xffff0000, v142
	v_lshlrev_b32_e32 v184, 16, v143
	v_and_b32_e32 v185, 0xffff0000, v143
	v_rcp_f32_e32 v178, v178
	v_rcp_f32_e32 v179, v179
	v_rcp_f32_e32 v180, v180
	v_rcp_f32_e32 v181, v181
	v_rcp_f32_e32 v182, v182
	v_rcp_f32_e32 v183, v183
	v_rcp_f32_e32 v184, v184
	v_rcp_f32_e32 v185, v185
	v_lshlrev_b32_e32 v140, 16, v132
	v_and_b32_e32 v141, 0xffff0000, v132
	v_lshlrev_b32_e32 v142, 16, v133
	v_and_b32_e32 v143, 0xffff0000, v133
	v_lshlrev_b32_e32 v132, 16, v134
	v_and_b32_e32 v133, 0xffff0000, v134
	v_lshlrev_b32_e32 v134, 16, v135
	v_and_b32_e32 v135, 0xffff0000, v135
	v_pk_mul_f32 v[178:179], v[178:179], v[140:141]
	v_pk_mul_f32 v[180:181], v[180:181], v[142:143]
	v_pk_mul_f32 v[182:183], v[182:183], v[132:133]
	v_pk_mul_f32 v[184:185], v[184:185], v[134:135]
	v_pk_mul_f32 v[64:65], v[64:65], v[178:179]
	v_pk_mul_f32 v[66:67], v[66:67], v[180:181]
	v_pk_mul_f32 v[60:61], v[60:61], v[182:183]
	v_pk_mul_f32 v[62:63], v[62:63], v[184:185]
	v_lshlrev_b32_e32 v246, 16, v188
	v_and_b32_e32 v247, 0xffff0000, v188
	v_lshlrev_b32_e32 v248, 16, v189
	v_and_b32_e32 v249, 0xffff0000, v189
	v_lshlrev_b32_e32 v250, 16, v190
	v_and_b32_e32 v251, 0xffff0000, v190
	v_lshlrev_b32_e32 v252, 16, v191
	v_and_b32_e32 v253, 0xffff0000, v191
	v_rcp_f32_e32 v246, v246
	v_rcp_f32_e32 v247, v247
	v_rcp_f32_e32 v248, v248
	v_rcp_f32_e32 v249, v249
	v_rcp_f32_e32 v250, v250
	v_rcp_f32_e32 v251, v251
	v_rcp_f32_e32 v252, v252
	v_rcp_f32_e32 v253, v253
	v_lshlrev_b32_e32 v188, 16, v136
	v_and_b32_e32 v189, 0xffff0000, v136
	v_lshlrev_b32_e32 v190, 16, v137
	v_and_b32_e32 v191, 0xffff0000, v137
	v_lshlrev_b32_e32 v136, 16, v138
	v_and_b32_e32 v137, 0xffff0000, v138
	v_lshlrev_b32_e32 v138, 16, v139
	v_and_b32_e32 v139, 0xffff0000, v139
	v_pk_mul_f32 v[246:247], v[246:247], v[188:189]
	v_pk_mul_f32 v[248:249], v[248:249], v[190:191]
	v_pk_mul_f32 v[250:251], v[250:251], v[136:137]
	v_pk_mul_f32 v[252:253], v[252:253], v[138:139]
	v_pk_mul_f32 v[56:57], v[56:57], v[246:247]
	v_pk_mul_f32 v[58:59], v[58:59], v[248:249]
	v_pk_mul_f32 v[52:53], v[52:53], v[250:251]
	v_pk_mul_f32 v[54:55], v[54:55], v[252:253]
	s_waitcnt vmcnt(8)
	v_lshlrev_b32_e32 v178, 16, v200
	v_and_b32_e32 v179, 0xffff0000, v200
	v_lshlrev_b32_e32 v180, 16, v201
	v_and_b32_e32 v181, 0xffff0000, v201
	v_lshlrev_b32_e32 v182, 16, v202
	v_and_b32_e32 v183, 0xffff0000, v202
	v_lshlrev_b32_e32 v184, 16, v203
	v_and_b32_e32 v185, 0xffff0000, v203
	v_rcp_f32_e32 v178, v178
	v_rcp_f32_e32 v179, v179
	v_rcp_f32_e32 v180, v180
	v_rcp_f32_e32 v181, v181
	v_rcp_f32_e32 v182, v182
	v_rcp_f32_e32 v183, v183
	v_rcp_f32_e32 v184, v184
	v_rcp_f32_e32 v185, v185
	v_lshlrev_b32_e32 v200, 16, v192
	v_and_b32_e32 v201, 0xffff0000, v192
	v_lshlrev_b32_e32 v202, 16, v193
	v_and_b32_e32 v203, 0xffff0000, v193
	v_lshlrev_b32_e32 v192, 16, v194
	v_and_b32_e32 v193, 0xffff0000, v194
	v_lshlrev_b32_e32 v194, 16, v195
	v_and_b32_e32 v195, 0xffff0000, v195
	v_pk_mul_f32 v[178:179], v[178:179], v[200:201]
	v_pk_mul_f32 v[180:181], v[180:181], v[202:203]
	v_pk_mul_f32 v[182:183], v[182:183], v[192:193]
	v_pk_mul_f32 v[184:185], v[184:185], v[194:195]
	v_pk_mul_f32 v[48:49], v[48:49], v[178:179]
	v_pk_mul_f32 v[50:51], v[50:51], v[180:181]
	v_pk_mul_f32 v[44:45], v[44:45], v[182:183]
	v_pk_mul_f32 v[46:47], v[46:47], v[184:185]
	v_lshlrev_b32_e32 v246, 16, v204
	v_and_b32_e32 v247, 0xffff0000, v204
	v_lshlrev_b32_e32 v248, 16, v205
	v_and_b32_e32 v249, 0xffff0000, v205
	v_lshlrev_b32_e32 v250, 16, v206
	v_and_b32_e32 v251, 0xffff0000, v206
	v_lshlrev_b32_e32 v252, 16, v207
	v_and_b32_e32 v253, 0xffff0000, v207
	v_rcp_f32_e32 v246, v246
	v_rcp_f32_e32 v247, v247
	v_rcp_f32_e32 v248, v248
	v_rcp_f32_e32 v249, v249
	v_rcp_f32_e32 v250, v250
	v_rcp_f32_e32 v251, v251
	v_rcp_f32_e32 v252, v252
	v_rcp_f32_e32 v253, v253
	v_lshlrev_b32_e32 v204, 16, v196
	v_and_b32_e32 v205, 0xffff0000, v196
	v_lshlrev_b32_e32 v206, 16, v197
	v_and_b32_e32 v207, 0xffff0000, v197
	v_lshlrev_b32_e32 v196, 16, v198
	v_and_b32_e32 v197, 0xffff0000, v198
	v_lshlrev_b32_e32 v198, 16, v199
	v_and_b32_e32 v199, 0xffff0000, v199
	v_pk_mul_f32 v[246:247], v[246:247], v[204:205]
	v_pk_mul_f32 v[248:249], v[248:249], v[206:207]
	v_pk_mul_f32 v[250:251], v[250:251], v[196:197]
	v_pk_mul_f32 v[252:253], v[252:253], v[198:199]
	v_pk_mul_f32 v[40:41], v[40:41], v[246:247]
	v_pk_mul_f32 v[42:43], v[42:43], v[248:249]
	v_pk_mul_f32 v[36:37], v[36:37], v[250:251]
	v_pk_mul_f32 v[38:39], v[38:39], v[252:253]
	s_waitcnt vmcnt(4)
	v_lshlrev_b32_e32 v178, 16, v216
	v_and_b32_e32 v179, 0xffff0000, v216
	v_lshlrev_b32_e32 v180, 16, v217
	v_and_b32_e32 v181, 0xffff0000, v217
	v_lshlrev_b32_e32 v182, 16, v218
	v_and_b32_e32 v183, 0xffff0000, v218
	v_lshlrev_b32_e32 v184, 16, v219
	v_and_b32_e32 v185, 0xffff0000, v219
	v_rcp_f32_e32 v178, v178
	v_rcp_f32_e32 v179, v179
	v_rcp_f32_e32 v180, v180
	v_rcp_f32_e32 v181, v181
	v_rcp_f32_e32 v182, v182
	v_rcp_f32_e32 v183, v183
	v_rcp_f32_e32 v184, v184
	v_rcp_f32_e32 v185, v185
	v_lshlrev_b32_e32 v216, 16, v208
	v_and_b32_e32 v217, 0xffff0000, v208
	v_lshlrev_b32_e32 v218, 16, v209
	v_and_b32_e32 v219, 0xffff0000, v209
	v_lshlrev_b32_e32 v208, 16, v210
	v_and_b32_e32 v209, 0xffff0000, v210
	v_lshlrev_b32_e32 v210, 16, v211
	v_and_b32_e32 v211, 0xffff0000, v211
	v_pk_mul_f32 v[178:179], v[178:179], v[216:217]
	v_pk_mul_f32 v[180:181], v[180:181], v[218:219]
	v_pk_mul_f32 v[182:183], v[182:183], v[208:209]
	v_pk_mul_f32 v[184:185], v[184:185], v[210:211]
	v_pk_mul_f32 v[32:33], v[32:33], v[178:179]
	v_pk_mul_f32 v[34:35], v[34:35], v[180:181]
	v_pk_mul_f32 v[28:29], v[28:29], v[182:183]
	v_pk_mul_f32 v[30:31], v[30:31], v[184:185]
	v_lshlrev_b32_e32 v246, 16, v220
	v_and_b32_e32 v247, 0xffff0000, v220
	v_lshlrev_b32_e32 v248, 16, v221
	v_and_b32_e32 v249, 0xffff0000, v221
	v_lshlrev_b32_e32 v250, 16, v222
	v_and_b32_e32 v251, 0xffff0000, v222
	v_lshlrev_b32_e32 v252, 16, v223
	v_and_b32_e32 v253, 0xffff0000, v223
	v_rcp_f32_e32 v246, v246
	v_rcp_f32_e32 v247, v247
	v_rcp_f32_e32 v248, v248
	v_rcp_f32_e32 v249, v249
	v_rcp_f32_e32 v250, v250
	v_rcp_f32_e32 v251, v251
	v_rcp_f32_e32 v252, v252
	v_rcp_f32_e32 v253, v253
	v_lshlrev_b32_e32 v220, 16, v212
	v_and_b32_e32 v221, 0xffff0000, v212
	v_lshlrev_b32_e32 v222, 16, v213
	v_and_b32_e32 v223, 0xffff0000, v213
	v_lshlrev_b32_e32 v212, 16, v214
	v_and_b32_e32 v213, 0xffff0000, v214
	v_lshlrev_b32_e32 v214, 16, v215
	v_and_b32_e32 v215, 0xffff0000, v215
	v_pk_mul_f32 v[246:247], v[246:247], v[220:221]
	v_pk_mul_f32 v[248:249], v[248:249], v[222:223]
	v_pk_mul_f32 v[250:251], v[250:251], v[212:213]
	v_pk_mul_f32 v[252:253], v[252:253], v[214:215]
	v_pk_mul_f32 v[24:25], v[24:25], v[246:247]
	v_pk_mul_f32 v[26:27], v[26:27], v[248:249]
	v_pk_mul_f32 v[20:21], v[20:21], v[250:251]
	v_pk_mul_f32 v[22:23], v[22:23], v[252:253]
	s_waitcnt vmcnt(0)
	v_lshlrev_b32_e32 v178, 16, v232
	v_and_b32_e32 v179, 0xffff0000, v232
	v_lshlrev_b32_e32 v180, 16, v233
	v_and_b32_e32 v181, 0xffff0000, v233
	v_lshlrev_b32_e32 v182, 16, v234
	v_and_b32_e32 v183, 0xffff0000, v234
	v_lshlrev_b32_e32 v184, 16, v235
	v_and_b32_e32 v185, 0xffff0000, v235
	v_rcp_f32_e32 v178, v178
	v_rcp_f32_e32 v179, v179
	v_rcp_f32_e32 v180, v180
	v_rcp_f32_e32 v181, v181
	v_rcp_f32_e32 v182, v182
	v_rcp_f32_e32 v183, v183
	v_rcp_f32_e32 v184, v184
	v_rcp_f32_e32 v185, v185
	v_lshlrev_b32_e32 v232, 16, v224
	v_and_b32_e32 v233, 0xffff0000, v224
	v_lshlrev_b32_e32 v234, 16, v225
	v_and_b32_e32 v235, 0xffff0000, v225
	v_lshlrev_b32_e32 v224, 16, v226
	v_and_b32_e32 v225, 0xffff0000, v226
	v_lshlrev_b32_e32 v226, 16, v227
	v_and_b32_e32 v227, 0xffff0000, v227
	v_pk_mul_f32 v[178:179], v[178:179], v[232:233]
	v_pk_mul_f32 v[180:181], v[180:181], v[234:235]
	v_pk_mul_f32 v[182:183], v[182:183], v[224:225]
	v_pk_mul_f32 v[184:185], v[184:185], v[226:227]
	v_pk_mul_f32 v[16:17], v[16:17], v[178:179]
	v_pk_mul_f32 v[18:19], v[18:19], v[180:181]
	v_pk_mul_f32 v[12:13], v[12:13], v[182:183]
	v_pk_mul_f32 v[14:15], v[14:15], v[184:185]
	v_lshlrev_b32_e32 v246, 16, v236
	v_and_b32_e32 v247, 0xffff0000, v236
	v_lshlrev_b32_e32 v248, 16, v237
	v_and_b32_e32 v249, 0xffff0000, v237
	v_lshlrev_b32_e32 v250, 16, v238
	v_and_b32_e32 v251, 0xffff0000, v238
	v_lshlrev_b32_e32 v252, 16, v239
	v_and_b32_e32 v253, 0xffff0000, v239
	v_rcp_f32_e32 v246, v246
	v_rcp_f32_e32 v247, v247
	v_rcp_f32_e32 v248, v248
	v_rcp_f32_e32 v249, v249
	v_rcp_f32_e32 v250, v250
	v_rcp_f32_e32 v251, v251
	v_rcp_f32_e32 v252, v252
	v_rcp_f32_e32 v253, v253
	v_lshlrev_b32_e32 v236, 16, v228
	v_and_b32_e32 v237, 0xffff0000, v228
	v_lshlrev_b32_e32 v238, 16, v229
	v_and_b32_e32 v239, 0xffff0000, v229
	v_lshlrev_b32_e32 v228, 16, v230
	v_and_b32_e32 v229, 0xffff0000, v230
	v_lshlrev_b32_e32 v230, 16, v231
	v_and_b32_e32 v231, 0xffff0000, v231
	v_pk_mul_f32 v[246:247], v[246:247], v[236:237]
	v_pk_mul_f32 v[248:249], v[248:249], v[238:239]
	v_pk_mul_f32 v[250:251], v[250:251], v[228:229]
	v_pk_mul_f32 v[252:253], v[252:253], v[230:231]
	v_pk_mul_f32 v[8:9], v[8:9], v[246:247]
	v_pk_mul_f32 v[10:11], v[10:11], v[248:249]
	v_pk_mul_f32 v[4:5], v[4:5], v[250:251]
	v_pk_mul_f32 v[6:7], v[6:7], v[252:253]
.Lhk_skipB:
	s_barrier
	s_add_u32 s60, s60, 0x100
	s_addc_u32 s61, s61, 0
	s_cmp_ge_i32 s2, s88
	s_cbranch_scc1 .LBB0_601
	s_mov_b32 s64, s2
	s_branch .LBB0_597
